# v48 + masked-tile skip extended: finishSM (exp, row sum, P packing) of a wholly masked tile skipped with its row sum set to 0; in the unit tail a wholly masked last tile skips its whole softmax (alpha
# speedup vs baseline: 1.0074x; 1.0050x over previous
.Lmskip_fox_0:
	s_waitcnt lgkmcnt(0)
	s_sub_i32 s0, s11, s27
	s_cmp_ge_i32 s0, 159
	s_cbranch_scc1 .Lfskip_fox_1
	v_exp_f32_e32 v226, v66
	v_add_f32_e32 v66, 0, v215
	v_add_f32_e32 v66, v217, v66
	v_add_f32_e32 v66, v213, v66
	v_add_f32_e32 v66, v216, v66
	v_add_f32_e32 v66, v211, v66
	v_add_f32_e32 v66, v214, v66
	v_add_f32_e32 v66, v210, v66
	v_add_f32_e32 v66, v212, v66
	v_add_f32_e32 v66, v207, v66
	v_add_f32_e32 v66, v209, v66
	v_add_f32_e32 v66, v205, v66
	v_add_f32_e32 v66, v208, v66
	v_exp_f32_e32 v80, v80
	v_add_f32_e32 v66, v203, v66
	v_exp_f32_e32 v1, v1
	v_add_f32_e32 v66, v206, v66
	v_exp_f32_e32 v78, v78
	v_add_f32_e32 v66, v202, v66
	v_exp_f32_e32 v79, v79
	v_add_f32_e32 v66, v204, v66
	v_exp_f32_e32 v76, v76
	v_add_f32_e32 v66, v80, v66
	v_exp_f32_e32 v77, v77
	v_add_f32_e32 v66, v1, v66
	v_exp_f32_e32 v81, v74
	v_add_f32_e32 v66, v78, v66
	v_exp_f32_e32 v219, v75
	v_add_f32_e32 v66, v79, v66
	v_exp_f32_e32 v220, v72
	v_add_f32_e32 v66, v76, v66
	v_exp_f32_e32 v221, v73
	v_add_f32_e32 v66, v77, v66
	v_exp_f32_e32 v222, v70
	v_add_f32_e32 v66, v81, v66
	v_exp_f32_e32 v223, v71
	v_add_f32_e32 v66, v219, v66
	v_exp_f32_e32 v224, v68
	v_add_f32_e32 v66, v220, v66
	v_exp_f32_e32 v225, v69
	v_add_f32_e32 v66, v221, v66
	v_add_f32_e32 v66, v222, v66
	v_exp_f32_e32 v227, v67
	v_add_f32_e32 v66, v223, v66
	v_add_f32_e32 v66, v224, v66
	v_add_f32_e32 v66, v225, v66
	v_add_f32_e32 v66, v226, v66
	v_add_f32_e32 v200, v227, v66
	v_mov_b32_e32 v201, v200
	v_cvt_pk_bf16_f32 v66, v215, v217
	v_cvt_pk_bf16_f32 v67, v213, v216
	v_cvt_pk_bf16_f32 v68, v211, v214
	v_cvt_pk_bf16_f32 v69, v210, v212
	v_cvt_pk_bf16_f32 v70, v207, v209
	v_cvt_pk_bf16_f32 v71, v205, v208
	v_cvt_pk_bf16_f32 v72, v203, v206
	v_cvt_pk_bf16_f32 v73, v202, v204
	v_cvt_pk_bf16_f32 v74, v80, v1
	v_cvt_pk_bf16_f32 v75, v78, v79
	v_cvt_pk_bf16_f32 v76, v76, v77
	v_cvt_pk_bf16_f32 v77, v81, v219
	v_cvt_pk_bf16_f32 v78, v220, v221
	v_cvt_pk_bf16_f32 v79, v222, v223
	v_cvt_pk_bf16_f32 v80, v224, v225
	v_cvt_pk_bf16_f32 v81, v226, v227
	s_nop 1
	v_permlane32_swap_b32_e32 v200, v201
	v_permlane32_swap_b32_e32 v66, v68
	v_permlane32_swap_b32_e32 v67, v69
	v_permlane32_swap_b32_e32 v70, v72
	v_permlane32_swap_b32_e32 v71, v73
	v_permlane32_swap_b32_e32 v74, v76
	v_permlane32_swap_b32_e32 v75, v77
	v_permlane32_swap_b32_e32 v78, v80
	v_permlane32_swap_b32_e32 v79, v81
	ds_read_b64_tr_b16 v[202:203], v183 offset:0
	ds_read_b64_tr_b16 v[204:205], v183 offset:0x800
	ds_read_b64_tr_b16 v[206:207], v183 offset:0x1000
	ds_read_b64_tr_b16 v[208:209], v183 offset:0x1800
	ds_read_b64_tr_b16 v[210:211], v183 offset:0x2000
	ds_read_b64_tr_b16 v[212:213], v183 offset:0x2800
	ds_read_b64_tr_b16 v[214:215], v183 offset:0x3000
	ds_read_b64_tr_b16 v[216:217], v183 offset:0x3800
	s_nop 0
	s_waitcnt lgkmcnt(6)
	v_mfma_f32_32x32x16_bf16 v[50:65], v[66:69], v[202:205], v[50:65]
	ds_read_b64_tr_b16 v[202:203], v183 offset:0x200
	ds_read_b64_tr_b16 v[204:205], v183 offset:0xa00
	s_waitcnt lgkmcnt(6)
	v_mfma_f32_32x32x16_bf16 v[50:65], v[70:73], v[206:209], v[50:65]
	ds_read_b64_tr_b16 v[206:207], v183 offset:0x1200
	ds_read_b64_tr_b16 v[208:209], v183 offset:0x1a00
	s_waitcnt lgkmcnt(6)
	v_mfma_f32_32x32x16_bf16 v[50:65], v[74:77], v[210:213], v[50:65]
	ds_read_b64_tr_b16 v[210:211], v183 offset:0x2200
	ds_read_b64_tr_b16 v[212:213], v183 offset:0x2a00
	s_waitcnt lgkmcnt(6)
	v_mfma_f32_32x32x16_bf16 v[50:65], v[78:81], v[214:217], v[50:65]
	ds_read_b64_tr_b16 v[214:215], v183 offset:0x3200
	ds_read_b64_tr_b16 v[216:217], v183 offset:0x3a00
	s_waitcnt lgkmcnt(6)
	v_mfma_f32_32x32x16_bf16 v[34:49], v[66:69], v[202:205], v[34:49]
	ds_read_b64_tr_b16 v[202:203], v183 offset:0x400
	ds_read_b64_tr_b16 v[204:205], v183 offset:0xc00
	s_waitcnt lgkmcnt(6)
	v_mfma_f32_32x32x16_bf16 v[34:49], v[70:73], v[206:209], v[34:49]
	ds_read_b64_tr_b16 v[206:207], v183 offset:0x1400
	ds_read_b64_tr_b16 v[208:209], v183 offset:0x1c00
	s_waitcnt lgkmcnt(6)
	v_mfma_f32_32x32x16_bf16 v[34:49], v[74:77], v[210:213], v[34:49]
	ds_read_b64_tr_b16 v[210:211], v183 offset:0x2400
	ds_read_b64_tr_b16 v[212:213], v183 offset:0x2c00
	s_waitcnt lgkmcnt(6)
	v_mfma_f32_32x32x16_bf16 v[34:49], v[78:81], v[214:217], v[34:49]
	ds_read_b64_tr_b16 v[214:215], v183 offset:0x3400
	ds_read_b64_tr_b16 v[216:217], v183 offset:0x3c00
	s_waitcnt lgkmcnt(6)
	v_mfma_f32_32x32x16_bf16 v[18:33], v[66:69], v[202:205], v[18:33]
	ds_read_b64_tr_b16 v[202:203], v183 offset:0x600
	ds_read_b64_tr_b16 v[204:205], v183 offset:0xe00
	s_waitcnt lgkmcnt(6)
	v_mfma_f32_32x32x16_bf16 v[18:33], v[70:73], v[206:209], v[18:33]
	ds_read_b64_tr_b16 v[206:207], v183 offset:0x1600
	ds_read_b64_tr_b16 v[208:209], v183 offset:0x1e00
	s_waitcnt lgkmcnt(6)
	v_mfma_f32_32x32x16_bf16 v[18:33], v[74:77], v[210:213], v[18:33]
	ds_read_b64_tr_b16 v[210:211], v183 offset:0x2600
	ds_read_b64_tr_b16 v[212:213], v183 offset:0x2e00
	s_waitcnt lgkmcnt(6)
	v_mfma_f32_32x32x16_bf16 v[18:33], v[78:81], v[214:217], v[18:33]
	ds_read_b64_tr_b16 v[214:215], v183 offset:0x3600
	ds_read_b64_tr_b16 v[216:217], v183 offset:0x3e00
	s_waitcnt lgkmcnt(6)
	v_mfma_f32_32x32x16_bf16 v[2:17], v[66:69], v[202:205], v[2:17]
	s_waitcnt lgkmcnt(4)
	v_mfma_f32_32x32x16_bf16 v[2:17], v[70:73], v[206:209], v[2:17]
	s_waitcnt lgkmcnt(2)
	v_mfma_f32_32x32x16_bf16 v[2:17], v[74:77], v[210:213], v[2:17]
	s_waitcnt lgkmcnt(0)
	v_mfma_f32_32x32x16_bf16 v[2:17], v[78:81], v[214:217], v[2:17]

.Lmskip_fox_2:
	s_waitcnt lgkmcnt(0)
	s_sub_i32 s0, s11, s27
	s_cmp_ge_i32 s0, 95
	s_cbranch_scc1 .Lfskip_fox_3
	v_exp_f32_e32 v222, v104
	v_add_f32_e32 v104, 0, v196
	v_add_f32_e32 v104, v203, v104
	v_add_f32_e32 v104, v112, v104
	v_add_f32_e32 v104, v202, v104
	v_add_f32_e32 v104, v110, v104
	v_add_f32_e32 v104, v113, v104
	v_add_f32_e32 v104, v109, v104
	v_add_f32_e32 v104, v111, v104
	v_add_f32_e32 v104, v103, v104
	v_add_f32_e32 v104, v107, v104
	v_add_f32_e32 v104, v101, v104
	v_add_f32_e32 v104, v106, v104
	v_add_f32_e32 v104, v99, v104
	v_exp_f32_e32 v223, v105
	v_add_f32_e32 v104, v102, v104
	v_exp_f32_e32 v208, v208
	v_add_f32_e32 v104, v98, v104
	v_exp_f32_e32 v209, v209
	v_add_f32_e32 v104, v100, v104
	v_exp_f32_e32 v210, v210
	v_add_f32_e32 v104, v222, v104
	v_exp_f32_e32 v211, v211
	v_add_f32_e32 v104, v223, v104
	v_exp_f32_e32 v212, v212
	v_add_f32_e32 v104, v208, v104
	v_exp_f32_e32 v213, v213
	v_add_f32_e32 v104, v209, v104
	v_exp_f32_e32 v214, v214
	v_add_f32_e32 v104, v210, v104
	v_exp_f32_e32 v215, v215
	v_add_f32_e32 v104, v211, v104
	v_exp_f32_e32 v216, v216
	v_add_f32_e32 v104, v212, v104
	v_exp_f32_e32 v217, v217
	v_add_f32_e32 v104, v213, v104
	v_exp_f32_e32 v218, v218
	v_add_f32_e32 v104, v214, v104
	v_exp_f32_e32 v219, v219
	v_add_f32_e32 v104, v215, v104
	v_exp_f32_e32 v220, v220
	v_add_f32_e32 v104, v216, v104
	v_exp_f32_e32 v221, v221
	v_add_f32_e32 v104, v217, v104
	v_add_f32_e32 v104, v218, v104
	v_add_f32_e32 v104, v219, v104
	v_add_f32_e32 v104, v220, v104
	v_add_f32_e32 v104, v221, v104
	v_mov_b32_e32 v105, v104
	v_cvt_pk_bf16_f32 v204, v196, v203
	v_cvt_pk_bf16_f32 v205, v112, v202
	v_cvt_pk_bf16_f32 v206, v110, v113
	v_cvt_pk_bf16_f32 v207, v109, v111
	v_cvt_pk_bf16_f32 v110, v103, v107
	v_cvt_pk_bf16_f32 v111, v101, v106
	v_cvt_pk_bf16_f32 v112, v99, v102
	v_cvt_pk_bf16_f32 v113, v98, v100
	v_cvt_pk_bf16_f32 v98, v222, v223
	v_cvt_pk_bf16_f32 v99, v208, v209
	v_cvt_pk_bf16_f32 v100, v210, v211
	v_cvt_pk_bf16_f32 v101, v212, v213
	s_nop 1
	v_permlane32_swap_b32_e32 v104, v105
	v_permlane32_swap_b32_e32 v98, v100
	v_permlane32_swap_b32_e32 v99, v101
	v_cvt_pk_bf16_f32 v208, v214, v215
	v_cvt_pk_bf16_f32 v209, v216, v217
	v_cvt_pk_bf16_f32 v210, v218, v219
	v_cvt_pk_bf16_f32 v211, v220, v221
	v_permlane32_swap_b32_e32 v204, v206
	v_permlane32_swap_b32_e32 v205, v207
	v_permlane32_swap_b32_e32 v110, v112
	v_permlane32_swap_b32_e32 v111, v113
	v_permlane32_swap_b32_e32 v208, v210
	v_permlane32_swap_b32_e32 v209, v211
	ds_read_b64_tr_b16 v[212:213], v183 offset:0x4000
	ds_read_b64_tr_b16 v[214:215], v183 offset:0x4800
	ds_read_b64_tr_b16 v[216:217], v183 offset:0x5000
	ds_read_b64_tr_b16 v[218:219], v183 offset:0x5800
	ds_read_b64_tr_b16 v[220:221], v183 offset:0x6000
	ds_read_b64_tr_b16 v[222:223], v183 offset:0x6800
	ds_read_b64_tr_b16 v[224:225], v183 offset:0x7000
	ds_read_b64_tr_b16 v[226:227], v183 offset:0x7800
	s_nop 0
	s_waitcnt lgkmcnt(6)
	v_mfma_f32_32x32x16_bf16 v[50:65], v[204:207], v[212:215], v[50:65]
	ds_read_b64_tr_b16 v[212:213], v183 offset:0x4200
	ds_read_b64_tr_b16 v[214:215], v183 offset:0x4a00
	s_waitcnt lgkmcnt(6)
	v_mfma_f32_32x32x16_bf16 v[50:65], v[110:113], v[216:219], v[50:65]
	ds_read_b64_tr_b16 v[216:217], v183 offset:0x5200
	ds_read_b64_tr_b16 v[218:219], v183 offset:0x5a00
	s_waitcnt lgkmcnt(6)
	v_mfma_f32_32x32x16_bf16 v[50:65], v[98:101], v[220:223], v[50:65]
	ds_read_b64_tr_b16 v[220:221], v183 offset:0x6200
	ds_read_b64_tr_b16 v[222:223], v183 offset:0x6a00
	s_waitcnt lgkmcnt(6)
	v_mfma_f32_32x32x16_bf16 v[50:65], v[208:211], v[224:227], v[50:65]
	ds_read_b64_tr_b16 v[224:225], v183 offset:0x7200
	ds_read_b64_tr_b16 v[226:227], v183 offset:0x7a00
	s_waitcnt lgkmcnt(6)
	v_mfma_f32_32x32x16_bf16 v[34:49], v[204:207], v[212:215], v[34:49]
	ds_read_b64_tr_b16 v[212:213], v183 offset:0x4400
	ds_read_b64_tr_b16 v[214:215], v183 offset:0x4c00
	s_waitcnt lgkmcnt(6)
	v_mfma_f32_32x32x16_bf16 v[34:49], v[110:113], v[216:219], v[34:49]
	ds_read_b64_tr_b16 v[216:217], v183 offset:0x5400
	ds_read_b64_tr_b16 v[218:219], v183 offset:0x5c00
	s_waitcnt lgkmcnt(6)
	v_mfma_f32_32x32x16_bf16 v[34:49], v[98:101], v[220:223], v[34:49]
	ds_read_b64_tr_b16 v[220:221], v183 offset:0x6400
	ds_read_b64_tr_b16 v[222:223], v183 offset:0x6c00
	s_waitcnt lgkmcnt(6)
	v_mfma_f32_32x32x16_bf16 v[34:49], v[208:211], v[224:227], v[34:49]
	ds_read_b64_tr_b16 v[224:225], v183 offset:0x7400
	ds_read_b64_tr_b16 v[226:227], v183 offset:0x7c00
	s_waitcnt lgkmcnt(6)
	v_mfma_f32_32x32x16_bf16 v[18:33], v[204:207], v[212:215], v[18:33]
	ds_read_b64_tr_b16 v[212:213], v183 offset:0x4600
	ds_read_b64_tr_b16 v[214:215], v183 offset:0x4e00
	s_waitcnt lgkmcnt(6)
	v_mfma_f32_32x32x16_bf16 v[18:33], v[110:113], v[216:219], v[18:33]
	ds_read_b64_tr_b16 v[216:217], v183 offset:0x5600
	ds_read_b64_tr_b16 v[218:219], v183 offset:0x5e00
	s_waitcnt lgkmcnt(6)
	v_mfma_f32_32x32x16_bf16 v[18:33], v[98:101], v[220:223], v[18:33]
	ds_read_b64_tr_b16 v[220:221], v183 offset:0x6600
	ds_read_b64_tr_b16 v[222:223], v183 offset:0x6e00
	s_waitcnt lgkmcnt(6)
	v_mfma_f32_32x32x16_bf16 v[18:33], v[208:211], v[224:227], v[18:33]
	ds_read_b64_tr_b16 v[224:225], v183 offset:0x7600
	ds_read_b64_tr_b16 v[226:227], v183 offset:0x7e00
	s_waitcnt lgkmcnt(6)
	v_mfma_f32_32x32x16_bf16 v[2:17], v[204:207], v[212:215], v[2:17]
	s_waitcnt lgkmcnt(4)
	v_mfma_f32_32x32x16_bf16 v[2:17], v[110:113], v[216:219], v[2:17]
	s_waitcnt lgkmcnt(2)
	v_mfma_f32_32x32x16_bf16 v[2:17], v[98:101], v[220:223], v[2:17]
	s_waitcnt lgkmcnt(0)
	v_mfma_f32_32x32x16_bf16 v[2:17], v[208:211], v[224:227], v[2:17]

.Lfskip_fox_5:
	v_mov_b32_e32 v1, 0
	v_mov_b32_e32 v114, 0
	s_branch .Lmskip_fox_5
.Ltskip_fox:
	v_mov_b32_e32 v66, 0
	v_mov_b32_e32 v67, 0
	v_mov_b32_e32 v96, 1.0
	v_readlane_b32 s88, v242, 2
	s_movk_i32 s93, 0x6018
	s_mov_b32 s92, 0xf800000
	s_mov_b64 s[90:91], s[16:17]
	v_readlane_b32 s89, v242, 3
	v_readlane_b32 s86, v242, 0
	s_movk_i32 s83, 0x6000
	s_mov_b32 s56, s30
	v_readlane_b32 s87, v242, 1
	v_readlane_b32 s25, v243, 63
	s_branch .Lmskip_fox_6
.Lfskip_fox_3:
	v_mov_b32_e32 v104, 0
	v_mov_b32_e32 v105, 0
	s_branch .Lmskip_fox_3
.Lfskip_fox_1:
	v_mov_b32_e32 v200, 0
	v_mov_b32_e32 v201, 0
	s_branch .Lmskip_fox_1

.Lmskip_fox_4:
	s_waitcnt vmcnt(0) lgkmcnt(0)
	s_cmp_ge_i32 s9, 160
	s_cbranch_scc1 .Lfskip_fox_5
	v_exp_f32_e32 v81, v1
	v_add_f32_e32 v1, 0, v215
	v_add_f32_e32 v1, v217, v1
	v_add_f32_e32 v1, v213, v1
	v_add_f32_e32 v1, v216, v1
	v_add_f32_e32 v1, v211, v1
	v_add_f32_e32 v1, v214, v1
	v_add_f32_e32 v1, v210, v1
	v_add_f32_e32 v1, v212, v1
	v_add_f32_e32 v1, v207, v1
	v_add_f32_e32 v1, v209, v1
	v_add_f32_e32 v1, v205, v1
	v_add_f32_e32 v1, v208, v1
	v_exp_f32_e32 v80, v80
	v_add_f32_e32 v1, v203, v1
	v_add_f32_e32 v1, v206, v1
	v_exp_f32_e32 v78, v78
	v_add_f32_e32 v1, v202, v1
	v_exp_f32_e32 v79, v79
	v_add_f32_e32 v1, v204, v1
	v_exp_f32_e32 v76, v76
	v_add_f32_e32 v1, v80, v1
	v_exp_f32_e32 v77, v77
	v_add_f32_e32 v1, v81, v1
	v_exp_f32_e32 v115, v74
	v_add_f32_e32 v1, v78, v1
	v_exp_f32_e32 v116, v75
	v_add_f32_e32 v1, v79, v1
	v_exp_f32_e32 v117, v72
	v_add_f32_e32 v1, v76, v1
	v_exp_f32_e32 v118, v73
	v_add_f32_e32 v1, v77, v1
	v_exp_f32_e32 v119, v70
	v_add_f32_e32 v1, v115, v1
	v_exp_f32_e32 v120, v71
	v_add_f32_e32 v1, v116, v1
	v_exp_f32_e32 v121, v68
	v_add_f32_e32 v1, v117, v1
	v_exp_f32_e32 v122, v69
	v_add_f32_e32 v1, v118, v1
	v_exp_f32_e32 v123, v66
	v_add_f32_e32 v1, v119, v1
	v_exp_f32_e32 v124, v67
	v_add_f32_e32 v1, v120, v1
	v_add_f32_e32 v1, v121, v1
	v_add_f32_e32 v1, v122, v1
	v_add_f32_e32 v1, v123, v1
	v_add_f32_e32 v1, v124, v1
	v_mov_b32_e32 v114, v1
	v_cvt_pk_bf16_f32 v66, v215, v217
	v_cvt_pk_bf16_f32 v67, v213, v216
	v_cvt_pk_bf16_f32 v68, v211, v214
	v_cvt_pk_bf16_f32 v69, v210, v212
	v_cvt_pk_bf16_f32 v70, v207, v209
	v_cvt_pk_bf16_f32 v71, v205, v208
	v_cvt_pk_bf16_f32 v72, v203, v206
	v_cvt_pk_bf16_f32 v73, v202, v204
	v_cvt_pk_bf16_f32 v74, v80, v81
	v_cvt_pk_bf16_f32 v75, v78, v79
	v_cvt_pk_bf16_f32 v76, v76, v77
	v_cvt_pk_bf16_f32 v77, v115, v116
	v_cvt_pk_bf16_f32 v78, v117, v118
	v_cvt_pk_bf16_f32 v79, v119, v120
	v_cvt_pk_bf16_f32 v80, v121, v122
	v_cvt_pk_bf16_f32 v81, v123, v124
	s_nop 1
	v_permlane32_swap_b32_e32 v1, v114
	v_permlane32_swap_b32_e32 v66, v68
	v_permlane32_swap_b32_e32 v67, v69
	v_permlane32_swap_b32_e32 v70, v72
	v_permlane32_swap_b32_e32 v71, v73
	v_permlane32_swap_b32_e32 v74, v76
	v_permlane32_swap_b32_e32 v75, v77
	v_permlane32_swap_b32_e32 v78, v80
	v_permlane32_swap_b32_e32 v79, v81
	ds_read_b64_tr_b16 v[116:117], v183 offset:0
	ds_read_b64_tr_b16 v[118:119], v183 offset:0x800
	ds_read_b64_tr_b16 v[120:121], v183 offset:0x1000
	ds_read_b64_tr_b16 v[122:123], v183 offset:0x1800
	ds_read_b64_tr_b16 v[124:125], v183 offset:0x2000
	ds_read_b64_tr_b16 v[126:127], v183 offset:0x2800
	ds_read_b64_tr_b16 v[128:129], v183 offset:0x3000
	ds_read_b64_tr_b16 v[130:131], v183 offset:0x3800
	s_nop 0
	s_waitcnt lgkmcnt(6)
	v_mfma_f32_32x32x16_bf16 v[50:65], v[66:69], v[116:119], v[50:65]
	ds_read_b64_tr_b16 v[116:117], v183 offset:0x200
	ds_read_b64_tr_b16 v[118:119], v183 offset:0xa00
	s_waitcnt lgkmcnt(6)
	v_mfma_f32_32x32x16_bf16 v[50:65], v[70:73], v[120:123], v[50:65]
	ds_read_b64_tr_b16 v[120:121], v183 offset:0x1200
	ds_read_b64_tr_b16 v[122:123], v183 offset:0x1a00
	s_waitcnt lgkmcnt(6)
	v_mfma_f32_32x32x16_bf16 v[50:65], v[74:77], v[124:127], v[50:65]
	ds_read_b64_tr_b16 v[124:125], v183 offset:0x2200
	ds_read_b64_tr_b16 v[126:127], v183 offset:0x2a00
	s_waitcnt lgkmcnt(6)
	v_mfma_f32_32x32x16_bf16 v[50:65], v[78:81], v[128:131], v[50:65]
	ds_read_b64_tr_b16 v[128:129], v183 offset:0x3200
	ds_read_b64_tr_b16 v[130:131], v183 offset:0x3a00
	s_waitcnt lgkmcnt(6)
	v_mfma_f32_32x32x16_bf16 v[34:49], v[66:69], v[116:119], v[34:49]
	ds_read_b64_tr_b16 v[116:117], v183 offset:0x400
	ds_read_b64_tr_b16 v[118:119], v183 offset:0xc00
	s_waitcnt lgkmcnt(6)
	v_mfma_f32_32x32x16_bf16 v[34:49], v[70:73], v[120:123], v[34:49]
	ds_read_b64_tr_b16 v[120:121], v183 offset:0x1400
	ds_read_b64_tr_b16 v[122:123], v183 offset:0x1c00
	s_waitcnt lgkmcnt(6)
	v_mfma_f32_32x32x16_bf16 v[34:49], v[74:77], v[124:127], v[34:49]
	ds_read_b64_tr_b16 v[124:125], v183 offset:0x2400
	ds_read_b64_tr_b16 v[126:127], v183 offset:0x2c00
	s_waitcnt lgkmcnt(6)
	v_mfma_f32_32x32x16_bf16 v[34:49], v[78:81], v[128:131], v[34:49]
	ds_read_b64_tr_b16 v[128:129], v183 offset:0x3400
	ds_read_b64_tr_b16 v[130:131], v183 offset:0x3c00
	s_waitcnt lgkmcnt(6)
	v_mfma_f32_32x32x16_bf16 v[18:33], v[66:69], v[116:119], v[18:33]
	ds_read_b64_tr_b16 v[116:117], v183 offset:0x600
	ds_read_b64_tr_b16 v[118:119], v183 offset:0xe00
	s_waitcnt lgkmcnt(6)
	v_mfma_f32_32x32x16_bf16 v[18:33], v[70:73], v[120:123], v[18:33]
	ds_read_b64_tr_b16 v[120:121], v183 offset:0x1600
	ds_read_b64_tr_b16 v[122:123], v183 offset:0x1e00
	s_waitcnt lgkmcnt(6)
	v_mfma_f32_32x32x16_bf16 v[18:33], v[74:77], v[124:127], v[18:33]
	ds_read_b64_tr_b16 v[124:125], v183 offset:0x2600
	ds_read_b64_tr_b16 v[126:127], v183 offset:0x2e00
	s_waitcnt lgkmcnt(6)
	v_mfma_f32_32x32x16_bf16 v[18:33], v[78:81], v[128:131], v[18:33]
	ds_read_b64_tr_b16 v[128:129], v183 offset:0x3600
	ds_read_b64_tr_b16 v[130:131], v183 offset:0x3e00
	s_waitcnt lgkmcnt(6)
	v_mfma_f32_32x32x16_bf16 v[2:17], v[66:69], v[116:119], v[2:17]
	s_waitcnt lgkmcnt(4)
	v_mfma_f32_32x32x16_bf16 v[2:17], v[70:73], v[120:123], v[2:17]
	s_waitcnt lgkmcnt(2)
	v_mfma_f32_32x32x16_bf16 v[2:17], v[74:77], v[124:127], v[2:17]
	s_waitcnt lgkmcnt(0)
	v_mfma_f32_32x32x16_bf16 v[2:17], v[78:81], v[128:131], v[2:17]
.Lmskip_fox_5:
	s_cmp_ge_i32 s9, 96
	s_cbranch_scc1 .Ltskip_fox
	s_lshl_b32 s1, s25, 6
	s_sub_i32 s0, s1, 64
	s_lshl_b32 s2, s0, 2
	s_add_i32 s2, s2, 0
	v_lshl_add_u32 v66, v186, 2, s2
	v_add_u32_e32 v66, 0x10800, v66
	s_add_i32 s1, s1, -1
	s_cmp_gt_i32 s1, s27
	ds_read_b128 v[116:119], v66 offset:128
	ds_read_b128 v[120:123], v66
	ds_read_b128 v[68:71], v66 offset:32
	ds_read_b128 v[124:127], v66 offset:160
	ds_read_b128 v[72:75], v66 offset:64
	ds_read_b128 v[128:131], v66 offset:192
	ds_read_b128 v[76:79], v66 offset:96
	ds_read_b128 v[132:135], v66 offset:224
	s_waitcnt lgkmcnt(6)
	v_xor_b32_e32 v81, 0x80000000, v123
	v_xor_b32_e32 v80, 0x80000000, v122
	s_waitcnt lgkmcnt(5)
	v_xor_b32_e32 v123, 0x80000000, v71
	v_xor_b32_e32 v122, 0x80000000, v70
	s_waitcnt lgkmcnt(1)
	v_xor_b32_e32 v137, 0x80000000, v75
	v_xor_b32_e32 v136, 0x80000000, v74
	v_fma_f32 v66, v110, s12, -v76
	v_fma_f32 v67, v111, s12, -v77
	v_fma_f32 v70, v106, s12, -v72
	v_fma_f32 v71, v107, s12, -v73
	v_fma_f32 v74, v102, s12, -v68
	v_fma_f32 v75, v103, s12, -v69
	v_fma_f32 v68, v112, s12, -v78
	v_fma_f32 v69, v113, s12, -v79
	v_fma_f32 v76, v104, s12, v122
	v_fma_f32 v77, v105, s12, v123
	v_fma_f32 v78, v100, s12, v80
	v_fma_f32 v79, v101, s12, v81
	v_xor_b32_e32 v101, 0x80000000, v119
	v_xor_b32_e32 v100, 0x80000000, v118
	v_xor_b32_e32 v103, 0x80000000, v127
	v_xor_b32_e32 v102, 0x80000000, v126
	v_xor_b32_e32 v105, 0x80000000, v131
	v_xor_b32_e32 v104, 0x80000000, v130
	s_waitcnt lgkmcnt(0)
	v_xor_b32_e32 v107, 0x80000000, v135
	v_xor_b32_e32 v106, 0x80000000, v134
	v_fma_f32 v72, v108, s12, v136
	v_fma_f32 v73, v109, s12, v137
	v_fma_f32 v80, v98, s12, -v120
	v_fma_f32 v81, v99, s12, -v121
	v_fma_f32 v94, v94, s12, -v132
	v_fma_f32 v95, v95, s12, -v133
	v_fma_f32 v90, v90, s12, -v128
	v_fma_f32 v91, v91, s12, -v129
	v_fma_f32 v98, v86, s12, -v124
	v_fma_f32 v99, v87, s12, -v125
	v_fma_f32 v86, v96, s12, v106
	v_fma_f32 v87, v97, s12, v107
	v_fma_f32 v92, v92, s12, v104
	v_fma_f32 v93, v93, s12, v105
	v_fma_f32 v88, v88, s12, v102
	v_fma_f32 v89, v89, s12, v103
	v_fma_f32 v84, v84, s12, v100
	v_fma_f32 v85, v85, s12, v101
	v_fma_f32 v82, v82, s12, -v116
	v_fma_f32 v83, v83, s12, -v117
	s_cbranch_scc0 .LBB0_666
	v_subrev_u32_e32 v96, s0, v187
	v_cmp_gt_i32_e64 s[92:93], 26, v96
	v_cmp_gt_i32_e64 s[94:95], 27, v96
	v_cmp_gt_i32_e64 s[90:91], 25, v96
	s_and_b64 s[92:93], s[94:95], s[92:93]
	v_cmp_gt_i32_e64 s[88:89], 24, v96
	s_and_b64 s[90:91], s[92:93], s[90:91]
	v_cmp_gt_i32_e64 s[86:87], 19, v96
	s_and_b64 s[88:89], s[90:91], s[88:89]
	v_cmp_gt_i32_e64 s[84:85], 18, v96
	s_and_b64 s[86:87], s[88:89], s[86:87]
	v_cmp_gt_i32_e64 s[82:83], 17, v96
	s_and_b64 s[84:85], s[86:87], s[84:85]
	v_cmp_gt_i32_e64 s[80:81], 16, v96
	s_and_b64 s[82:83], s[84:85], s[82:83]
	v_cmp_gt_i32_e64 s[78:79], 11, v96
	s_and_b64 s[80:81], s[82:83], s[80:81]
	v_cmp_gt_i32_e64 s[76:77], 10, v96
	s_and_b64 s[78:79], s[80:81], s[78:79]
	v_cmp_gt_i32_e64 s[74:75], 9, v96
	s_and_b64 s[76:77], s[78:79], s[76:77]
	v_cmp_gt_i32_e64 s[72:73], 8, v96
	s_and_b64 s[74:75], s[76:77], s[74:75]
	v_cmp_gt_i32_e64 s[70:71], 3, v96
	s_and_b64 s[72:73], s[74:75], s[72:73]
	v_cmp_gt_i32_e64 s[68:69], 2, v96
	s_and_b64 s[70:71], s[72:73], s[70:71]
	v_cmp_gt_i32_e64 s[2:3], 1, v96
	s_and_b64 s[68:69], s[70:71], s[68:69]
	v_cmp_gt_i32_e64 s[0:1], 0, v96
	s_and_b64 s[2:3], s[68:69], s[2:3]
	s_and_b64 s[0:1], s[2:3], s[0:1]
	v_cmp_gt_i32_e64 s[66:67], 58, v96
	v_cndmask_b32_e64 v80, v80, v175, s[0:1]
	v_cmp_gt_i32_e64 s[0:1], 59, v96
	v_cmp_gt_i32_e64 s[64:65], 57, v96
	v_cmp_gt_i32_e64 s[62:63], 56, v96
	v_cndmask_b32_e64 v87, v87, v175, s[0:1]
	s_and_b64 s[0:1], s[0:1], s[66:67]
	v_cndmask_b32_e64 v86, v86, v175, s[0:1]
	s_and_b64 s[0:1], s[0:1], s[64:65]
	v_cmp_gt_i32_e64 s[60:61], 51, v96
	v_cndmask_b32_e64 v95, v95, v175, s[0:1]
	s_and_b64 s[0:1], s[0:1], s[62:63]
	v_cmp_gt_i32_e64 s[58:59], 50, v96
	v_cndmask_b32_e64 v94, v94, v175, s[0:1]
	s_and_b64 s[0:1], s[0:1], s[60:61]
	v_cmp_gt_i32_e64 s[56:57], 49, v96
	v_cndmask_b32_e64 v93, v93, v175, s[0:1]
	s_and_b64 s[0:1], s[0:1], s[58:59]
	v_cmp_gt_i32_e64 s[54:55], 48, v96
	v_cndmask_b32_e64 v92, v92, v175, s[0:1]
	s_and_b64 s[0:1], s[0:1], s[56:57]
	v_cmp_gt_i32_e64 s[52:53], 43, v96
	v_cndmask_b32_e64 v91, v91, v175, s[0:1]
	s_and_b64 s[0:1], s[0:1], s[54:55]
	v_cmp_gt_i32_e64 s[50:51], 42, v96
	v_cndmask_b32_e64 v90, v90, v175, s[0:1]
	s_and_b64 s[0:1], s[0:1], s[52:53]
	v_cmp_gt_i32_e64 s[48:49], 41, v96
	v_cndmask_b32_e64 v89, v89, v175, s[0:1]
	s_and_b64 s[0:1], s[0:1], s[50:51]
	v_cmp_gt_i32_e64 s[46:47], 40, v96
	v_cndmask_b32_e64 v88, v88, v175, s[0:1]
	s_and_b64 s[0:1], s[0:1], s[48:49]
	v_cmp_gt_i32_e64 s[44:45], 35, v96
	v_cndmask_b32_e64 v99, v99, v175, s[0:1]
	s_and_b64 s[0:1], s[0:1], s[46:47]
	v_cmp_gt_i32_e64 s[42:43], 34, v96
	v_cndmask_b32_e64 v98, v98, v175, s[0:1]
	s_and_b64 s[0:1], s[0:1], s[44:45]
	v_cmp_gt_i32_e64 s[40:41], 33, v96
	v_cndmask_b32_e64 v85, v85, v175, s[0:1]
	s_and_b64 s[0:1], s[0:1], s[42:43]
	v_cmp_gt_i32_e32 vcc, 32, v96
	v_cndmask_b32_e64 v84, v84, v175, s[0:1]
	s_and_b64 s[0:1], s[0:1], s[40:41]
	v_cndmask_b32_e64 v66, v66, v175, s[88:89]
	v_readlane_b32 s88, v242, 2
	s_and_b64 vcc, s[0:1], vcc
	v_cndmask_b32_e64 v69, v69, v175, s[94:95]
	v_cndmask_b32_e64 v68, v68, v175, s[92:93]
	s_movk_i32 s93, 0x6018
	s_mov_b32 s92, 0xf800000
	v_cndmask_b32_e64 v67, v67, v175, s[90:91]
	s_mov_b64 s[90:91], s[16:17]
	v_readlane_b32 s89, v242, 3
	v_cndmask_b32_e64 v73, v73, v175, s[86:87]
	v_readlane_b32 s86, v242, 0
	v_cndmask_b32_e64 v72, v72, v175, s[84:85]
	v_cndmask_b32_e64 v71, v71, v175, s[82:83]
	s_movk_i32 s83, 0x6000
	v_cndmask_b32_e64 v70, v70, v175, s[80:81]
	v_cndmask_b32_e64 v77, v77, v175, s[78:79]
	v_cndmask_b32_e64 v76, v76, v175, s[76:77]
	v_cndmask_b32_e64 v75, v75, v175, s[74:75]
	v_cndmask_b32_e64 v74, v74, v175, s[72:73]
	v_cndmask_b32_e64 v79, v79, v175, s[70:71]
	v_cndmask_b32_e64 v78, v78, v175, s[68:69]
	v_cndmask_b32_e64 v81, v81, v175, s[2:3]
	s_mov_b32 s56, s30
	v_cndmask_b32_e64 v83, v83, v175, s[0:1]
	v_cndmask_b32_e32 v82, v82, v175, vcc
	v_readlane_b32 s87, v242, 1

.Lmskip_dif_0:
	s_waitcnt lgkmcnt(0)
	s_sub_i32 s0, s9, s25
	s_cmp_ge_i32 s0, 159
	s_cbranch_scc1 .Lfskip_dif_1
	v_exp_f32_e32 v206, v132
	v_add_f32_e32 v132, 0, v197
	v_add_f32_e32 v132, v199, v132
	v_add_f32_e32 v132, v195, v132
	v_add_f32_e32 v132, v198, v132
	v_add_f32_e32 v132, v193, v132
	v_add_f32_e32 v132, v196, v132
	v_add_f32_e32 v132, v192, v132
	v_add_f32_e32 v132, v194, v132
	v_add_f32_e32 v132, v189, v132
	v_add_f32_e32 v132, v191, v132
	v_add_f32_e32 v132, v187, v132
	v_add_f32_e32 v132, v190, v132
	v_exp_f32_e32 v146, v146
	v_add_f32_e32 v132, v185, v132
	v_exp_f32_e32 v147, v147
	v_add_f32_e32 v132, v188, v132
	v_exp_f32_e32 v144, v144
	v_add_f32_e32 v132, v184, v132
	v_exp_f32_e32 v145, v145
	v_add_f32_e32 v132, v186, v132
	v_exp_f32_e32 v142, v142
	v_add_f32_e32 v132, v146, v132
	v_exp_f32_e32 v143, v143
	v_add_f32_e32 v132, v147, v132
	v_exp_f32_e32 v181, v140
	v_add_f32_e32 v132, v144, v132
	v_exp_f32_e32 v183, v141
	v_add_f32_e32 v132, v145, v132
	v_exp_f32_e32 v200, v138
	v_add_f32_e32 v132, v142, v132
	v_exp_f32_e32 v201, v139
	v_add_f32_e32 v132, v143, v132
	v_exp_f32_e32 v202, v136
	v_add_f32_e32 v132, v181, v132
	v_exp_f32_e32 v203, v137
	v_add_f32_e32 v132, v183, v132
	v_exp_f32_e32 v204, v134
	v_add_f32_e32 v132, v200, v132
	v_exp_f32_e32 v205, v135
	v_add_f32_e32 v132, v201, v132
	v_add_f32_e32 v132, v202, v132
	v_exp_f32_e32 v207, v133
	v_add_f32_e32 v132, v203, v132
	v_add_f32_e32 v132, v204, v132
	v_add_f32_e32 v132, v205, v132
	v_add_f32_e32 v132, v206, v132
	v_add_f32_e32 v179, v207, v132
	v_mov_b32_e32 v180, v179
	s_nop 1
	v_permlane32_swap_b32_e32 v179, v180
	v_cvt_pk_bf16_f32 v132, v197, v199
	v_cvt_pk_bf16_f32 v133, v195, v198
	v_cvt_pk_bf16_f32 v134, v193, v196
	v_cvt_pk_bf16_f32 v135, v192, v194
	v_cvt_pk_bf16_f32 v136, v189, v191
	v_cvt_pk_bf16_f32 v137, v187, v190
	v_cvt_pk_bf16_f32 v138, v185, v188
	v_cvt_pk_bf16_f32 v139, v184, v186
	v_cvt_pk_bf16_f32 v140, v146, v147
	v_cvt_pk_bf16_f32 v141, v144, v145
	v_cvt_pk_bf16_f32 v142, v142, v143
	v_cvt_pk_bf16_f32 v143, v181, v183
	v_cvt_pk_bf16_f32 v144, v200, v201
	v_cvt_pk_bf16_f32 v145, v202, v203
	v_cvt_pk_bf16_f32 v146, v204, v205
	v_cvt_pk_bf16_f32 v147, v206, v207
	s_nop 0
	v_permlane32_swap_b32_e32 v132, v134
	v_permlane32_swap_b32_e32 v133, v135
	v_permlane32_swap_b32_e32 v136, v138
	v_permlane32_swap_b32_e32 v137, v139
	v_permlane32_swap_b32_e32 v140, v142
	v_permlane32_swap_b32_e32 v141, v143
	v_permlane32_swap_b32_e32 v144, v146
	v_permlane32_swap_b32_e32 v145, v147
	ds_read_b64_tr_b16 v[184:185], v153 offset:0
	ds_read_b64_tr_b16 v[186:187], v153 offset:0x800
	ds_read_b64_tr_b16 v[188:189], v153 offset:0x1000
	ds_read_b64_tr_b16 v[190:191], v153 offset:0x1800
	ds_read_b64_tr_b16 v[192:193], v153 offset:0x2000
	ds_read_b64_tr_b16 v[194:195], v153 offset:0x2800
	ds_read_b64_tr_b16 v[196:197], v153 offset:0x3000
	ds_read_b64_tr_b16 v[198:199], v153 offset:0x3800
	s_nop 0
	s_waitcnt lgkmcnt(6)
	v_mfma_f32_32x32x16_bf16 v[50:65], v[132:135], v[184:187], v[50:65]
	ds_read_b64_tr_b16 v[184:185], v153 offset:0x200
	ds_read_b64_tr_b16 v[186:187], v153 offset:0xa00
	s_waitcnt lgkmcnt(6)
	v_mfma_f32_32x32x16_bf16 v[50:65], v[136:139], v[188:191], v[50:65]
	ds_read_b64_tr_b16 v[188:189], v153 offset:0x1200
	ds_read_b64_tr_b16 v[190:191], v153 offset:0x1a00
	s_waitcnt lgkmcnt(6)
	v_mfma_f32_32x32x16_bf16 v[50:65], v[140:143], v[192:195], v[50:65]
	ds_read_b64_tr_b16 v[192:193], v153 offset:0x2200
	ds_read_b64_tr_b16 v[194:195], v153 offset:0x2a00
	s_waitcnt lgkmcnt(6)
	v_mfma_f32_32x32x16_bf16 v[50:65], v[144:147], v[196:199], v[50:65]
	ds_read_b64_tr_b16 v[196:197], v153 offset:0x3200
	ds_read_b64_tr_b16 v[198:199], v153 offset:0x3a00
	s_waitcnt lgkmcnt(6)
	v_mfma_f32_32x32x16_bf16 v[34:49], v[132:135], v[184:187], v[34:49]
	ds_read_b64_tr_b16 v[184:185], v153 offset:0x400
	ds_read_b64_tr_b16 v[186:187], v153 offset:0xc00
	s_waitcnt lgkmcnt(6)
	v_mfma_f32_32x32x16_bf16 v[34:49], v[136:139], v[188:191], v[34:49]
	ds_read_b64_tr_b16 v[188:189], v153 offset:0x1400
	ds_read_b64_tr_b16 v[190:191], v153 offset:0x1c00
	s_waitcnt lgkmcnt(6)
	v_mfma_f32_32x32x16_bf16 v[34:49], v[140:143], v[192:195], v[34:49]
	ds_read_b64_tr_b16 v[192:193], v153 offset:0x2400
	ds_read_b64_tr_b16 v[194:195], v153 offset:0x2c00
	s_waitcnt lgkmcnt(6)
	v_mfma_f32_32x32x16_bf16 v[34:49], v[144:147], v[196:199], v[34:49]
	ds_read_b64_tr_b16 v[196:197], v153 offset:0x3400
	ds_read_b64_tr_b16 v[198:199], v153 offset:0x3c00
	s_waitcnt lgkmcnt(6)
	v_mfma_f32_32x32x16_bf16 v[18:33], v[132:135], v[184:187], v[18:33]
	ds_read_b64_tr_b16 v[184:185], v153 offset:0x600
	ds_read_b64_tr_b16 v[186:187], v153 offset:0xe00
	s_waitcnt lgkmcnt(6)
	v_mfma_f32_32x32x16_bf16 v[18:33], v[136:139], v[188:191], v[18:33]
	ds_read_b64_tr_b16 v[188:189], v153 offset:0x1600
	ds_read_b64_tr_b16 v[190:191], v153 offset:0x1e00
	s_waitcnt lgkmcnt(6)
	v_mfma_f32_32x32x16_bf16 v[18:33], v[140:143], v[192:195], v[18:33]
	ds_read_b64_tr_b16 v[192:193], v153 offset:0x2600
	ds_read_b64_tr_b16 v[194:195], v153 offset:0x2e00
	s_waitcnt lgkmcnt(6)
	v_mfma_f32_32x32x16_bf16 v[18:33], v[144:147], v[196:199], v[18:33]
	ds_read_b64_tr_b16 v[196:197], v153 offset:0x3600
	ds_read_b64_tr_b16 v[198:199], v153 offset:0x3e00
	s_waitcnt lgkmcnt(6)
	v_mfma_f32_32x32x16_bf16 v[2:17], v[132:135], v[184:187], v[2:17]
	s_waitcnt lgkmcnt(4)
	v_mfma_f32_32x32x16_bf16 v[2:17], v[136:139], v[188:191], v[2:17]
	s_waitcnt lgkmcnt(2)
	v_mfma_f32_32x32x16_bf16 v[2:17], v[140:143], v[192:195], v[2:17]
	s_waitcnt lgkmcnt(0)
	v_mfma_f32_32x32x16_bf16 v[2:17], v[144:147], v[196:199], v[2:17]

.Lmskip_dif_2:
	s_waitcnt lgkmcnt(0)
	s_sub_i32 s0, s9, s25
	s_cmp_ge_i32 s0, 95
	s_cbranch_scc1 .Lfskip_dif_3
	v_add_f32_e32 v182, 0, v146
	v_add_f32_e32 v182, v168, v182
	v_add_f32_e32 v182, v144, v182
	v_add_f32_e32 v182, v147, v182
	v_add_f32_e32 v182, v142, v182
	v_add_f32_e32 v182, v145, v182
	v_add_f32_e32 v182, v141, v182
	v_add_f32_e32 v182, v143, v182
	v_add_f32_e32 v182, v138, v182
	v_add_f32_e32 v182, v140, v182
	v_add_f32_e32 v182, v136, v182
	v_add_f32_e32 v182, v139, v182
	v_exp_f32_e32 v199, v184
	v_add_f32_e32 v182, v134, v182
	v_exp_f32_e32 v200, v185
	v_add_f32_e32 v182, v137, v182
	v_exp_f32_e32 v201, v186
	v_add_f32_e32 v182, v133, v182
	v_exp_f32_e32 v202, v187
	v_add_f32_e32 v182, v135, v182
	v_exp_f32_e32 v188, v188
	v_add_f32_e32 v182, v199, v182
	v_exp_f32_e32 v189, v189
	v_add_f32_e32 v182, v200, v182
	v_exp_f32_e32 v190, v190
	v_add_f32_e32 v182, v201, v182
	v_exp_f32_e32 v191, v191
	v_add_f32_e32 v182, v202, v182
	v_exp_f32_e32 v192, v192
	v_add_f32_e32 v182, v188, v182
	v_exp_f32_e32 v193, v193
	v_add_f32_e32 v182, v189, v182
	v_exp_f32_e32 v194, v194
	v_add_f32_e32 v182, v190, v182
	v_exp_f32_e32 v195, v195
	v_add_f32_e32 v182, v191, v182
	v_exp_f32_e32 v196, v196
	v_add_f32_e32 v182, v192, v182
	v_exp_f32_e32 v197, v197
	v_add_f32_e32 v182, v193, v182
	v_exp_f32_e32 v198, v198
	v_add_f32_e32 v182, v194, v182
	v_exp_f32_e32 v203, v183
	v_add_f32_e32 v182, v195, v182
	v_add_f32_e32 v182, v196, v182
	v_add_f32_e32 v182, v197, v182
	v_add_f32_e32 v182, v198, v182
	v_add_f32_e32 v182, v203, v182
	v_mov_b32_e32 v183, v182
	s_nop 1
	v_permlane32_swap_b32_e32 v182, v183
	v_cvt_pk_bf16_f32 v184, v146, v168
	v_cvt_pk_bf16_f32 v185, v144, v147
	v_cvt_pk_bf16_f32 v186, v142, v145
	v_cvt_pk_bf16_f32 v187, v141, v143
	v_cvt_pk_bf16_f32 v138, v138, v140
	v_cvt_pk_bf16_f32 v139, v136, v139
	v_cvt_pk_bf16_f32 v140, v134, v137
	v_cvt_pk_bf16_f32 v141, v133, v135
	v_cvt_pk_bf16_f32 v134, v199, v200
	v_cvt_pk_bf16_f32 v135, v201, v202
	v_cvt_pk_bf16_f32 v136, v188, v189
	v_cvt_pk_bf16_f32 v137, v190, v191
	v_cvt_pk_bf16_f32 v142, v192, v193
	v_cvt_pk_bf16_f32 v143, v194, v195
	v_cvt_pk_bf16_f32 v144, v196, v197
	v_cvt_pk_bf16_f32 v145, v198, v203
	s_nop 0
	v_permlane32_swap_b32_e32 v184, v186
	v_permlane32_swap_b32_e32 v185, v187
	v_permlane32_swap_b32_e32 v138, v140
	v_permlane32_swap_b32_e32 v139, v141
	v_permlane32_swap_b32_e32 v134, v136
	v_permlane32_swap_b32_e32 v135, v137
	v_permlane32_swap_b32_e32 v142, v144
	v_permlane32_swap_b32_e32 v143, v145
	ds_read_b64_tr_b16 v[188:189], v153 offset:0x4000
	ds_read_b64_tr_b16 v[190:191], v153 offset:0x4800
	ds_read_b64_tr_b16 v[192:193], v153 offset:0x5000
	ds_read_b64_tr_b16 v[194:195], v153 offset:0x5800
	ds_read_b64_tr_b16 v[196:197], v153 offset:0x6000
	ds_read_b64_tr_b16 v[198:199], v153 offset:0x6800
	ds_read_b64_tr_b16 v[200:201], v153 offset:0x7000
	ds_read_b64_tr_b16 v[202:203], v153 offset:0x7800
	s_nop 0
	s_waitcnt lgkmcnt(6)
	v_mfma_f32_32x32x16_bf16 v[50:65], v[184:187], v[188:191], v[50:65]
	ds_read_b64_tr_b16 v[188:189], v153 offset:0x4200
	ds_read_b64_tr_b16 v[190:191], v153 offset:0x4a00
	s_waitcnt lgkmcnt(6)
	v_mfma_f32_32x32x16_bf16 v[50:65], v[138:141], v[192:195], v[50:65]
	ds_read_b64_tr_b16 v[192:193], v153 offset:0x5200
	ds_read_b64_tr_b16 v[194:195], v153 offset:0x5a00
	s_waitcnt lgkmcnt(6)
	v_mfma_f32_32x32x16_bf16 v[50:65], v[134:137], v[196:199], v[50:65]
	ds_read_b64_tr_b16 v[196:197], v153 offset:0x6200
	ds_read_b64_tr_b16 v[198:199], v153 offset:0x6a00
	s_waitcnt lgkmcnt(6)
	v_mfma_f32_32x32x16_bf16 v[50:65], v[142:145], v[200:203], v[50:65]
	ds_read_b64_tr_b16 v[200:201], v153 offset:0x7200
	ds_read_b64_tr_b16 v[202:203], v153 offset:0x7a00
	s_waitcnt lgkmcnt(6)
	v_mfma_f32_32x32x16_bf16 v[34:49], v[184:187], v[188:191], v[34:49]
	ds_read_b64_tr_b16 v[188:189], v153 offset:0x4400
	ds_read_b64_tr_b16 v[190:191], v153 offset:0x4c00
	s_waitcnt lgkmcnt(6)
	v_mfma_f32_32x32x16_bf16 v[34:49], v[138:141], v[192:195], v[34:49]
	ds_read_b64_tr_b16 v[192:193], v153 offset:0x5400
	ds_read_b64_tr_b16 v[194:195], v153 offset:0x5c00
	s_waitcnt lgkmcnt(6)
	v_mfma_f32_32x32x16_bf16 v[34:49], v[134:137], v[196:199], v[34:49]
	ds_read_b64_tr_b16 v[196:197], v153 offset:0x6400
	ds_read_b64_tr_b16 v[198:199], v153 offset:0x6c00
	s_waitcnt lgkmcnt(6)
	v_mfma_f32_32x32x16_bf16 v[34:49], v[142:145], v[200:203], v[34:49]
	ds_read_b64_tr_b16 v[200:201], v153 offset:0x7400
	ds_read_b64_tr_b16 v[202:203], v153 offset:0x7c00
	s_waitcnt lgkmcnt(6)
	v_mfma_f32_32x32x16_bf16 v[18:33], v[184:187], v[188:191], v[18:33]
	ds_read_b64_tr_b16 v[188:189], v153 offset:0x4600
	ds_read_b64_tr_b16 v[190:191], v153 offset:0x4e00
	s_waitcnt lgkmcnt(6)
	v_mfma_f32_32x32x16_bf16 v[18:33], v[138:141], v[192:195], v[18:33]
	ds_read_b64_tr_b16 v[192:193], v153 offset:0x5600
	ds_read_b64_tr_b16 v[194:195], v153 offset:0x5e00
	s_waitcnt lgkmcnt(6)
	v_mfma_f32_32x32x16_bf16 v[18:33], v[134:137], v[196:199], v[18:33]
	ds_read_b64_tr_b16 v[196:197], v153 offset:0x6600
	ds_read_b64_tr_b16 v[198:199], v153 offset:0x6e00
	s_waitcnt lgkmcnt(6)
	v_mfma_f32_32x32x16_bf16 v[18:33], v[142:145], v[200:203], v[18:33]
	ds_read_b64_tr_b16 v[200:201], v153 offset:0x7600
	ds_read_b64_tr_b16 v[202:203], v153 offset:0x7e00
	s_waitcnt lgkmcnt(6)
	v_mfma_f32_32x32x16_bf16 v[2:17], v[184:187], v[188:191], v[2:17]
	s_waitcnt lgkmcnt(4)
	v_mfma_f32_32x32x16_bf16 v[2:17], v[138:141], v[192:195], v[2:17]
	s_waitcnt lgkmcnt(2)
	v_mfma_f32_32x32x16_bf16 v[2:17], v[134:137], v[196:199], v[2:17]
	s_waitcnt lgkmcnt(0)
	v_mfma_f32_32x32x16_bf16 v[2:17], v[142:145], v[200:203], v[2:17]

.Lfskip_dif_5:
	v_mov_b32_e32 v98, 0
	v_mov_b32_e32 v99, 0
	s_branch .Lmskip_dif_5
.Ltskip_dif:
	v_mov_b32_e32 v66, 0
	v_mov_b32_e32 v67, 0
	v_mov_b32_e32 v100, 1.0
	v_readlane_b32 s88, v242, 2
	v_readlane_b32 s25, v243, 63
	v_readlane_b32 s86, v242, 0
	v_readlane_b32 s89, v242, 3
	s_mov_b64 s[90:91], s[16:17]
	s_movk_i32 s83, 0x6000
	s_mov_b32 s92, 0xf800000
	s_movk_i32 s93, 0x6018
	s_mov_b32 s56, s30
	v_readlane_b32 s87, v242, 1
	s_branch .Lmskip_dif_6
.Lfskip_dif_3:
	v_mov_b32_e32 v182, 0
	v_mov_b32_e32 v183, 0
	s_branch .Lmskip_dif_3
.Lfskip_dif_1:
	v_mov_b32_e32 v179, 0
	v_mov_b32_e32 v180, 0
	s_branch .Lmskip_dif_1

.Lmskip_dif_4:
	s_waitcnt vmcnt(0) lgkmcnt(0)
	s_cmp_ge_i32 s9, 160
	s_cbranch_scc1 .Lfskip_dif_5
	v_add_f32_e32 v98, 0, v197
	v_add_f32_e32 v98, v199, v98
	v_add_f32_e32 v98, v195, v98
	v_add_f32_e32 v98, v198, v98
	v_add_f32_e32 v98, v193, v98
	v_add_f32_e32 v98, v196, v98
	v_add_f32_e32 v98, v192, v98
	v_add_f32_e32 v98, v194, v98
	v_add_f32_e32 v98, v189, v98
	v_add_f32_e32 v98, v191, v98
	v_add_f32_e32 v98, v187, v98
	v_add_f32_e32 v98, v190, v98
	v_exp_f32_e32 v108, v146
	v_add_f32_e32 v98, v185, v98
	v_exp_f32_e32 v109, v147
	v_add_f32_e32 v98, v188, v98
	v_exp_f32_e32 v110, v144
	v_add_f32_e32 v98, v184, v98
	v_exp_f32_e32 v111, v145
	v_add_f32_e32 v98, v186, v98
	v_exp_f32_e32 v112, v142
	v_add_f32_e32 v98, v108, v98
	v_exp_f32_e32 v113, v143
	v_add_f32_e32 v98, v109, v98
	v_exp_f32_e32 v115, v140
	v_add_f32_e32 v98, v110, v98
	v_exp_f32_e32 v116, v141
	v_add_f32_e32 v98, v111, v98
	v_exp_f32_e32 v117, v138
	v_add_f32_e32 v98, v112, v98
	v_exp_f32_e32 v118, v139
	v_add_f32_e32 v98, v113, v98
	v_exp_f32_e32 v119, v136
	v_add_f32_e32 v98, v115, v98
	v_exp_f32_e32 v120, v137
	v_add_f32_e32 v98, v116, v98
	v_exp_f32_e32 v121, v134
	v_add_f32_e32 v98, v117, v98
	v_exp_f32_e32 v122, v135
	v_add_f32_e32 v98, v118, v98
	v_exp_f32_e32 v123, v132
	v_add_f32_e32 v98, v119, v98
	v_exp_f32_e32 v124, v133
	v_add_f32_e32 v98, v120, v98
	v_add_f32_e32 v98, v121, v98
	v_add_f32_e32 v98, v122, v98
	v_add_f32_e32 v98, v123, v98
	v_add_f32_e32 v98, v124, v98
	v_mov_b32_e32 v99, v98
	s_nop 1
	v_permlane32_swap_b32_e32 v98, v99
	v_cvt_pk_bf16_f32 v100, v197, v199
	v_cvt_pk_bf16_f32 v101, v195, v198
	v_cvt_pk_bf16_f32 v102, v193, v196
	v_cvt_pk_bf16_f32 v103, v192, v194
	v_cvt_pk_bf16_f32 v104, v189, v191
	v_cvt_pk_bf16_f32 v105, v187, v190
	v_cvt_pk_bf16_f32 v106, v185, v188
	v_cvt_pk_bf16_f32 v107, v184, v186
	v_cvt_pk_bf16_f32 v108, v108, v109
	v_cvt_pk_bf16_f32 v109, v110, v111
	v_cvt_pk_bf16_f32 v110, v112, v113
	v_cvt_pk_bf16_f32 v111, v115, v116
	v_cvt_pk_bf16_f32 v116, v117, v118
	v_cvt_pk_bf16_f32 v117, v119, v120
	v_cvt_pk_bf16_f32 v118, v121, v122
	v_cvt_pk_bf16_f32 v119, v123, v124
	s_nop 0
	v_permlane32_swap_b32_e32 v100, v102
	v_permlane32_swap_b32_e32 v101, v103
	v_permlane32_swap_b32_e32 v104, v106
	v_permlane32_swap_b32_e32 v105, v107
	v_permlane32_swap_b32_e32 v108, v110
	v_permlane32_swap_b32_e32 v109, v111
	v_permlane32_swap_b32_e32 v116, v118
	v_permlane32_swap_b32_e32 v117, v119
	ds_read_b64_tr_b16 v[120:121], v153 offset:0
	ds_read_b64_tr_b16 v[122:123], v153 offset:0x800
	ds_read_b64_tr_b16 v[124:125], v153 offset:0x1000
	s_waitcnt vmcnt(0)
	ds_read_b64_tr_b16 v[126:127], v153 offset:0x1800
	ds_read_b64_tr_b16 v[128:129], v153 offset:0x2000
	ds_read_b64_tr_b16 v[130:131], v153 offset:0x2800
	ds_read_b64_tr_b16 v[132:133], v153 offset:0x3000
	ds_read_b64_tr_b16 v[134:135], v153 offset:0x3800
	s_waitcnt lgkmcnt(6)
	v_mfma_f32_32x32x16_bf16 v[50:65], v[100:103], v[120:123], v[50:65]
	ds_read_b64_tr_b16 v[120:121], v153 offset:0x200
	ds_read_b64_tr_b16 v[122:123], v153 offset:0xa00
	s_waitcnt lgkmcnt(6)
	v_mfma_f32_32x32x16_bf16 v[50:65], v[104:107], v[124:127], v[50:65]
	ds_read_b64_tr_b16 v[124:125], v153 offset:0x1200
	ds_read_b64_tr_b16 v[126:127], v153 offset:0x1a00
	s_waitcnt lgkmcnt(6)
	v_mfma_f32_32x32x16_bf16 v[50:65], v[108:111], v[128:131], v[50:65]
	ds_read_b64_tr_b16 v[128:129], v153 offset:0x2200
	ds_read_b64_tr_b16 v[130:131], v153 offset:0x2a00
	s_waitcnt lgkmcnt(6)
	v_mfma_f32_32x32x16_bf16 v[50:65], v[116:119], v[132:135], v[50:65]
	ds_read_b64_tr_b16 v[132:133], v153 offset:0x3200
	ds_read_b64_tr_b16 v[134:135], v153 offset:0x3a00
	s_waitcnt lgkmcnt(6)
	v_mfma_f32_32x32x16_bf16 v[34:49], v[100:103], v[120:123], v[34:49]
	ds_read_b64_tr_b16 v[120:121], v153 offset:0x400
	ds_read_b64_tr_b16 v[122:123], v153 offset:0xc00
	s_waitcnt lgkmcnt(6)
	v_mfma_f32_32x32x16_bf16 v[34:49], v[104:107], v[124:127], v[34:49]
	ds_read_b64_tr_b16 v[124:125], v153 offset:0x1400
	ds_read_b64_tr_b16 v[126:127], v153 offset:0x1c00
	s_waitcnt lgkmcnt(6)
	v_mfma_f32_32x32x16_bf16 v[34:49], v[108:111], v[128:131], v[34:49]
	ds_read_b64_tr_b16 v[128:129], v153 offset:0x2400
	ds_read_b64_tr_b16 v[130:131], v153 offset:0x2c00
	s_waitcnt lgkmcnt(6)
	v_mfma_f32_32x32x16_bf16 v[34:49], v[116:119], v[132:135], v[34:49]
	ds_read_b64_tr_b16 v[132:133], v153 offset:0x3400
	ds_read_b64_tr_b16 v[134:135], v153 offset:0x3c00
	s_waitcnt lgkmcnt(6)
	v_mfma_f32_32x32x16_bf16 v[18:33], v[100:103], v[120:123], v[18:33]
	ds_read_b64_tr_b16 v[120:121], v153 offset:0x600
	ds_read_b64_tr_b16 v[122:123], v153 offset:0xe00
	s_waitcnt lgkmcnt(6)
	v_mfma_f32_32x32x16_bf16 v[18:33], v[104:107], v[124:127], v[18:33]
	ds_read_b64_tr_b16 v[124:125], v153 offset:0x1600
	ds_read_b64_tr_b16 v[126:127], v153 offset:0x1e00
	s_waitcnt lgkmcnt(6)
	v_mfma_f32_32x32x16_bf16 v[18:33], v[108:111], v[128:131], v[18:33]
	ds_read_b64_tr_b16 v[128:129], v153 offset:0x2600
	ds_read_b64_tr_b16 v[130:131], v153 offset:0x2e00
	s_waitcnt lgkmcnt(6)
	v_mfma_f32_32x32x16_bf16 v[18:33], v[116:119], v[132:135], v[18:33]
	ds_read_b64_tr_b16 v[132:133], v153 offset:0x3600
	ds_read_b64_tr_b16 v[134:135], v153 offset:0x3e00
	s_waitcnt lgkmcnt(6)
	v_mfma_f32_32x32x16_bf16 v[2:17], v[100:103], v[120:123], v[2:17]
	s_waitcnt lgkmcnt(4)
	v_mfma_f32_32x32x16_bf16 v[2:17], v[104:107], v[124:127], v[2:17]
	s_waitcnt lgkmcnt(2)
	v_mfma_f32_32x32x16_bf16 v[2:17], v[108:111], v[128:131], v[2:17]
	s_waitcnt lgkmcnt(0)
	v_mfma_f32_32x32x16_bf16 v[2:17], v[116:119], v[132:135], v[2:17]
.Lmskip_dif_5:
	s_cmp_ge_i32 s9, 96
	s_cbranch_scc1 .Ltskip_dif
	s_lshl_b32 s0, s27, 6
	s_add_i32 s1, s0, -1
	s_cmp_gt_i32 s1, s25
	s_cbranch_scc0 .LBB0_844
	v_subrev_u32_e32 v100, s0, v156
	v_add_u32_e32 v100, 64, v100
	v_cmp_gt_i32_e64 s[90:91], 26, v100
	v_cmp_gt_i32_e64 s[92:93], 27, v100
	v_cmp_gt_i32_e64 s[88:89], 25, v100
	s_and_b64 s[90:91], s[92:93], s[90:91]
	v_cmp_gt_i32_e64 s[86:87], 24, v100
	s_and_b64 s[88:89], s[90:91], s[88:89]
	v_cmp_gt_i32_e64 s[84:85], 19, v100
	s_and_b64 s[86:87], s[88:89], s[86:87]
	v_cmp_gt_i32_e64 s[82:83], 18, v100
	s_and_b64 s[84:85], s[86:87], s[84:85]
	v_cmp_gt_i32_e64 s[80:81], 17, v100
	s_and_b64 s[82:83], s[84:85], s[82:83]
	v_cmp_gt_i32_e64 s[78:79], 16, v100
	s_and_b64 s[80:81], s[82:83], s[80:81]
	v_cmp_gt_i32_e64 s[76:77], 11, v100
	s_and_b64 s[78:79], s[80:81], s[78:79]
	v_cmp_gt_i32_e64 s[74:75], 10, v100
	s_and_b64 s[76:77], s[78:79], s[76:77]
	v_cmp_gt_i32_e64 s[72:73], 9, v100
	s_and_b64 s[74:75], s[76:77], s[74:75]
	v_cmp_gt_i32_e64 s[70:71], 8, v100
	s_and_b64 s[72:73], s[74:75], s[72:73]
	v_cmp_gt_i32_e64 s[68:69], 3, v100
	s_and_b64 s[70:71], s[72:73], s[70:71]
	v_cmp_gt_i32_e64 s[66:67], 2, v100
	s_and_b64 s[68:69], s[70:71], s[68:69]
	v_cmp_gt_i32_e64 s[2:3], 1, v100
	s_and_b64 s[66:67], s[68:69], s[66:67]
	v_cmp_gt_i32_e64 s[0:1], 0, v100
	s_and_b64 s[2:3], s[66:67], s[2:3]
	s_and_b64 s[0:1], s[2:3], s[0:1]
	v_cmp_gt_i32_e64 s[64:65], 58, v100
	v_cndmask_b32_e64 v82, v82, v175, s[0:1]
	v_cmp_gt_i32_e64 s[0:1], 59, v100
	v_cmp_gt_i32_e64 s[62:63], 57, v100
	v_cmp_gt_i32_e64 s[60:61], 56, v100
	v_cndmask_b32_e64 v81, v81, v175, s[0:1]
	s_and_b64 s[0:1], s[0:1], s[64:65]
	v_cndmask_b32_e64 v80, v80, v175, s[0:1]
	s_and_b64 s[0:1], s[0:1], s[62:63]
	v_cmp_gt_i32_e64 s[58:59], 51, v100
	v_cndmask_b32_e64 v79, v79, v175, s[0:1]
	s_and_b64 s[0:1], s[0:1], s[60:61]
	v_cmp_gt_i32_e64 s[56:57], 50, v100
	v_cndmask_b32_e64 v78, v78, v175, s[0:1]
	s_and_b64 s[0:1], s[0:1], s[58:59]
	v_cmp_gt_i32_e64 s[54:55], 49, v100
	v_cndmask_b32_e64 v77, v77, v175, s[0:1]
	s_and_b64 s[0:1], s[0:1], s[56:57]
	v_cmp_gt_i32_e64 s[52:53], 48, v100
	v_cndmask_b32_e64 v76, v76, v175, s[0:1]
	s_and_b64 s[0:1], s[0:1], s[54:55]
	v_cmp_gt_i32_e64 s[50:51], 43, v100
	v_cndmask_b32_e64 v75, v75, v175, s[0:1]
	s_and_b64 s[0:1], s[0:1], s[52:53]
	v_cmp_gt_i32_e64 s[48:49], 42, v100
	v_cndmask_b32_e64 v74, v74, v175, s[0:1]
	s_and_b64 s[0:1], s[0:1], s[50:51]
	v_cmp_gt_i32_e64 s[46:47], 41, v100
	v_cndmask_b32_e64 v73, v73, v175, s[0:1]
	s_and_b64 s[0:1], s[0:1], s[48:49]
	v_cmp_gt_i32_e64 s[44:45], 40, v100
	v_cndmask_b32_e64 v72, v72, v175, s[0:1]
	s_and_b64 s[0:1], s[0:1], s[46:47]
	v_cmp_gt_i32_e64 s[42:43], 35, v100
	v_cndmask_b32_e64 v71, v71, v175, s[0:1]
	s_and_b64 s[0:1], s[0:1], s[44:45]
	v_cmp_gt_i32_e64 s[40:41], 34, v100
	v_cndmask_b32_e64 v70, v70, v175, s[0:1]
	s_and_b64 s[0:1], s[0:1], s[42:43]
	v_cmp_gt_i32_e64 s[38:39], 33, v100
	v_cndmask_b32_e64 v69, v69, v175, s[0:1]
	s_and_b64 s[0:1], s[0:1], s[40:41]
	v_cmp_gt_i32_e32 vcc, 32, v100
	v_cndmask_b32_e64 v68, v68, v175, s[0:1]
	s_and_b64 s[0:1], s[0:1], s[38:39]
	s_and_b64 vcc, s[0:1], vcc
	v_cndmask_b32_e64 v97, v97, v175, s[92:93]
	v_cndmask_b32_e64 v96, v96, v175, s[90:91]
	v_cndmask_b32_e64 v95, v95, v175, s[88:89]
	v_cndmask_b32_e64 v94, v94, v175, s[86:87]
	v_cndmask_b32_e64 v93, v93, v175, s[84:85]
	v_cndmask_b32_e64 v92, v92, v175, s[82:83]
	v_cndmask_b32_e64 v91, v91, v175, s[80:81]
	v_cndmask_b32_e64 v90, v90, v175, s[78:79]
	v_cndmask_b32_e64 v89, v89, v175, s[76:77]
	v_cndmask_b32_e64 v88, v88, v175, s[74:75]
	v_cndmask_b32_e64 v87, v87, v175, s[72:73]
	v_cndmask_b32_e64 v86, v86, v175, s[70:71]
	v_cndmask_b32_e64 v85, v85, v175, s[68:69]
	v_cndmask_b32_e64 v84, v84, v175, s[66:67]
	v_cndmask_b32_e64 v83, v83, v175, s[2:3]
	v_cndmask_b32_e64 v67, v67, v175, s[0:1]
	v_cndmask_b32_e32 v66, v66, v175, vcc
